# stack: cache_tail 16-byte paired image stores + deferred queue-ticket reads in prologue, cache_tail and attention
# speedup vs baseline: 1.0012x; 1.0012x over previous
.LBB0_415:
	s_or_b64 exec, exec, s[26:27]
	v_readfirstlane_b32 s28, v90

.LBB0_417:
	v_mov_b32_e32 v46, v184
	v_mov_b32_e32 v1, 0
	v_cmp_eq_u32_e32 vcc, 0, v46
	s_and_saveexec_b64 s[26:27], vcc
	s_cbranch_execz .LBB0_421
	s_mov_b64 s[30:31], exec
	v_mbcnt_lo_u32_b32 v1, s30, 0
	v_mbcnt_hi_u32_b32 v1, s31, v1
	v_cmp_eq_u32_e32 vcc, 0, v1
	s_and_saveexec_b64 s[28:29], vcc
	s_cbranch_execz .LBB0_420
	s_bcnt1_i32_b64 s30, s[30:31]
	v_mov_b32_e32 v2, s30
	global_atomic_add v90, v35, v2, s[4:5] sc0

.LBB0_430:
	s_or_b64 exec, exec, s[26:27]
	v_readfirstlane_b32 s28, v90
	s_mov_b64 s[26:27], 0
